# MLA loop: one static s_setprio 1 for the older half (waves 0-3) for the whole key loop (mirror of the younger-half raise)
# speedup vs baseline: 1.0014x; 1.0014x over previous
.LBB0_42:
	v_add_u32_e32 v166, 0x8000, v166
	v_add_u32_e32 v167, 0x8000, v168
	v_add_u32_e32 v168, 0x8000, v170
	v_add_u32_e32 v169, 0x8000, v172
	v_add_u32_e32 v170, 0x8000, v174
	v_add_u32_e32 v171, 0x8000, v176
	v_add_u32_e32 v172, 0x8000, v178
	v_add_u32_e32 v173, 0x8000, v180
	v_mov_b32_e32 v174, v183
	v_mov_b32_e32 v175, v193
	v_mov_b32_e32 v176, v195
	v_mov_b32_e32 v177, v197
	v_mov_b32_e32 v178, v140
	v_mov_b32_e32 v179, v142
	v_add_u32_e32 v180, 0x100, v138
	v_add_u32_e32 v181, 0x180, v138
	v_mov_b32_e32 v182, v136
	s_add_u32 s98, s74, 0x13480000
	s_addc_u32 s99, s75, 0
	s_add_u32 s100, s74, 0xae04000
	s_addc_u32 s101, s75, 0
	v_mov_b32_e32 v144, v158
	v_mov_b32_e32 v145, v159
	v_mov_b32_e32 v146, v156
	v_mov_b32_e32 v147, v157
	v_mov_b32_e32 v148, v154
	v_mov_b32_e32 v149, v155
	v_mov_b32_e32 v150, v152
	v_mov_b32_e32 v151, v153
	v_mov_b32_e32 v152, v134
	v_mov_b32_e32 v153, v135
	v_mov_b32_e32 v154, v132
	v_mov_b32_e32 v155, v133
	v_mov_b32_e32 v156, v130
	v_mov_b32_e32 v157, v131
	v_mov_b32_e32 v158, v128
	v_mov_b32_e32 v159, v129
	v_mov_b32_e32 v242, v198
	v_sub_f32_e32 v198, 0, v222
	v_sub_f32_e32 v199, 0, v222
	v_sub_f32_e32 v200, 0, v222
	v_sub_f32_e32 v201, 0, v222
	v_sub_f32_e32 v202, 0, v222
	v_sub_f32_e32 v203, 0, v222
	v_sub_f32_e32 v204, 0, v222
	v_sub_f32_e32 v205, 0, v222
	v_sub_f32_e32 v206, 0, v222
	v_sub_f32_e32 v207, 0, v222
	v_sub_f32_e32 v208, 0, v222
	v_sub_f32_e32 v209, 0, v222
	v_sub_f32_e32 v210, 0, v222
	v_sub_f32_e32 v211, 0, v222
	v_sub_f32_e32 v212, 0, v222
	v_sub_f32_e32 v213, 0, v222
	v_mov_b32_e32 v128, v236
	v_mov_b32_e32 v129, v238
	v_mov_b32_e32 v130, v234
	v_mov_b32_e32 v131, v237
	v_mov_b32_e32 v132, v233
	v_mov_b32_e32 v133, v235
	v_mov_b32_e32 v134, v231
	v_mov_b32_e32 v135, v232
	v_mov_b32_e32 v136, v228
	v_mov_b32_e32 v137, v230
	v_mov_b32_e32 v138, v227
	v_mov_b32_e32 v139, v229
	v_mov_b32_e32 v140, v224
	v_mov_b32_e32 v141, v226
	v_mov_b32_e32 v142, v223
	v_mov_b32_e32 v143, v225
	v_readfirstlane_b32 s8, v191
	s_nop 3
	s_lshr_b32 s8, s8, 6
	s_cmp_ge_u32 s8, 4
	s_cbranch_scc1 .Lmla_prio
	s_setprio 1
